# FF1 epilogue: fold self-max canonicalisation (128 VALU/wave/tile), accumulator zeroing via v_mov_b64; on top of HID slab layout
# speedup vs baseline: 1.0163x; 1.0038x over previous
.LBB0_876:
	s_ashr_i32 s27, s26, 31
	s_lshl_b64 s[28:29], s[26:27], 19
	s_add_u32 s28, s66, s28
	s_addc_u32 s29, s67, s29
	s_and_b64 s[30:31], s[4:5], exec
	s_cselect_b32 s27, s29, s37
	s_cselect_b32 s57, s28, s36
	s_ashr_i32 s25, s24, 31
	s_lshl_b64 s[30:31], s[24:25], 19
	s_add_u32 s30, s72, s30
	s_addc_u32 s31, s73, s31
	s_and_b64 s[40:41], s[4:5], exec
	s_cselect_b32 s25, s31, s39
	s_cselect_b32 s58, s30, s38
	s_add_u32 s36, s36, 0x40080
	s_addc_u32 s37, s37, 0
	s_add_u32 s59, s38, 0x100
	s_addc_u32 s60, s39, 0
	s_mov_b32 s61, -2
	v_mov_b64_e32 v[0:1], 0
	v_mov_b64_e32 v[2:3], 0
	v_mov_b64_e32 v[4:5], 0
	v_mov_b64_e32 v[6:7], 0
	v_mov_b64_e32 v[8:9], 0
	v_mov_b64_e32 v[10:11], 0
	v_mov_b64_e32 v[12:13], 0
	v_mov_b64_e32 v[14:15], 0
	v_mov_b64_e32 v[16:17], 0
	v_mov_b64_e32 v[18:19], 0
	v_mov_b64_e32 v[20:21], 0
	v_mov_b64_e32 v[22:23], 0
	v_mov_b64_e32 v[24:25], 0
	v_mov_b64_e32 v[26:27], 0
	v_mov_b64_e32 v[28:29], 0
	v_mov_b64_e32 v[30:31], 0
	v_mov_b64_e32 v[32:33], 0
	v_mov_b64_e32 v[34:35], 0
	v_mov_b64_e32 v[36:37], 0
	v_mov_b64_e32 v[38:39], 0
	v_mov_b64_e32 v[40:41], 0
	v_mov_b64_e32 v[42:43], 0
	v_mov_b64_e32 v[44:45], 0
	v_mov_b64_e32 v[46:47], 0
	v_mov_b64_e32 v[48:49], 0
	v_mov_b64_e32 v[50:51], 0
	v_mov_b64_e32 v[52:53], 0
	v_mov_b64_e32 v[54:55], 0
	v_mov_b64_e32 v[56:57], 0
	v_mov_b64_e32 v[58:59], 0
	v_mov_b64_e32 v[60:61], 0
	v_mov_b64_e32 v[62:63], 0
	v_mov_b64_e32 v[64:65], 0
	v_mov_b64_e32 v[66:67], 0
	v_mov_b64_e32 v[68:69], 0
	v_mov_b64_e32 v[70:71], 0
	v_mov_b64_e32 v[72:73], 0
	v_mov_b64_e32 v[74:75], 0
	v_mov_b64_e32 v[76:77], 0
	v_mov_b64_e32 v[78:79], 0
	v_mov_b64_e32 v[80:81], 0
	v_mov_b64_e32 v[82:83], 0
	v_mov_b64_e32 v[84:85], 0
	v_mov_b64_e32 v[86:87], 0
	v_mov_b64_e32 v[88:89], 0
	v_mov_b64_e32 v[90:91], 0
	v_mov_b64_e32 v[92:93], 0
	v_mov_b64_e32 v[94:95], 0
	v_mov_b64_e32 v[96:97], 0
	v_mov_b64_e32 v[98:99], 0
	v_mov_b64_e32 v[100:101], 0
	v_mov_b64_e32 v[102:103], 0
	v_mov_b64_e32 v[104:105], 0
	v_mov_b64_e32 v[106:107], 0
	v_mov_b64_e32 v[108:109], 0
	v_mov_b64_e32 v[110:111], 0
	v_mov_b64_e32 v[112:113], 0
	v_mov_b64_e32 v[114:115], 0
	v_mov_b64_e32 v[116:117], 0
	v_mov_b64_e32 v[118:119], 0
	v_mov_b64_e32 v[120:121], 0
	v_mov_b64_e32 v[122:123], 0
	v_mov_b64_e32 v[124:125], 0
	v_mov_b64_e32 v[126:127], 0

.LBB0_880:
	v_lshl_add_u32 v150, s34, 8, v144
	v_lshl_or_b32 v152, s56, 8, v146
	v_ashrrev_i32_e32 v151, 31, v150
	v_max_f32_e32 v124, 0, v124
	v_max_f32_e32 v120, 0, v120
	v_max_f32_e32 v125, 0, v125
	v_max_f32_e32 v121, 0, v121
	v_max_f32_e32 v126, 0, v126
	v_max_f32_e32 v127, 0, v127
	v_ashrrev_i32_e32 v153, 31, v152
	v_lshlrev_b64 v[154:155], 7, v[150:151]
	v_pk_mul_f32 v[124:125], v[124:125], v[124:125]
	v_pk_mul_f32 v[120:121], v[120:121], v[120:121]
	v_max_f32_e32 v122, 0, v122
	v_max_f32_e32 v123, 0, v123
	v_pk_mul_f32 v[126:127], v[126:127], v[126:127]
	v_pk_mul_f32 v[156:157], v[122:123], v[122:123]
	v_cvt_pk_bf16_f32 v122, v124, v125
	v_cvt_pk_bf16_f32 v123, v126, v127
	v_cvt_pk_bf16_f32 v124, v120, v121
	v_lshl_add_u64 v[120:121], s[78:79], 0, v[154:155]
	v_and_b32_e32 v126, 0xfc0, v152
	v_and_b32_e32 v127, 63, v152
	v_lshlrev_b32_e32 v126, 16, v126
	v_lshl_or_b32 v126, v127, 1, v126
	v_mov_b32_e32 v127, 0
	v_cvt_pk_bf16_f32 v125, v156, v157
	v_lshl_add_u64 v[120:121], v[120:121], 0, v[126:127]
	v_max_f32_e32 v112, 0, v112
	v_max_f32_e32 v113, 0, v113
	global_store_dwordx4 v[120:121], v[122:125], off
	s_nop 1
	v_pk_mul_f32 v[122:123], v[112:113], v[112:113]
	v_max_f32_e32 v114, 0, v114
	v_max_f32_e32 v116, 0, v116
	v_max_f32_e32 v117, 0, v117
	v_max_f32_e32 v112, 0, v118
	v_max_f32_e32 v113, 0, v119
	v_max_f32_e32 v115, 0, v115
	v_pk_mul_f32 v[116:117], v[116:117], v[116:117]
	v_pk_mul_f32 v[118:119], v[112:113], v[112:113]
	v_pk_mul_f32 v[124:125], v[114:115], v[114:115]
	v_cvt_pk_bf16_f32 v112, v116, v117
	v_cvt_pk_bf16_f32 v113, v118, v119
	v_cvt_pk_bf16_f32 v114, v122, v123
	v_cvt_pk_bf16_f32 v115, v124, v125
	v_max_f32_e32 v104, 0, v104
	v_max_f32_e32 v105, 0, v105
	v_lshl_add_u64 v[200:201], v[120:121], 0, s[98:99]
	global_store_dwordx4 v[200:201], v[112:115], off
	s_nop 1
	v_or_b32_e32 v112, 16, v150
	v_pk_mul_f32 v[114:115], v[104:105], v[104:105]
	v_ashrrev_i32_e32 v113, 31, v112
	v_max_f32_e32 v108, 0, v108
	v_max_f32_e32 v109, 0, v109
	v_max_f32_e32 v106, 0, v106
	v_lshlrev_b64 v[112:113], 7, v[112:113]
	v_pk_mul_f32 v[108:109], v[108:109], v[108:109]
	v_max_f32_e32 v104, 0, v110
	v_max_f32_e32 v105, 0, v111
	v_max_f32_e32 v107, 0, v107
	v_pk_mul_f32 v[110:111], v[104:105], v[104:105]
	v_pk_mul_f32 v[116:117], v[106:107], v[106:107]
	v_cvt_pk_bf16_f32 v104, v108, v109
	v_lshl_add_u64 v[108:109], s[78:79], 0, v[112:113]
	v_cvt_pk_bf16_f32 v105, v110, v111
	v_cvt_pk_bf16_f32 v106, v114, v115
	v_cvt_pk_bf16_f32 v107, v116, v117
	v_lshl_add_u64 v[108:109], v[108:109], 0, v[126:127]
	v_max_f32_e32 v96, 0, v96
	v_max_f32_e32 v97, 0, v97
	global_store_dwordx4 v[108:109], v[104:107], off
	s_nop 1
	v_pk_mul_f32 v[104:105], v[96:97], v[96:97]
	v_max_f32_e32 v98, 0, v98
	v_max_f32_e32 v100, 0, v100
	v_max_f32_e32 v101, 0, v101
	v_max_f32_e32 v96, 0, v102
	v_max_f32_e32 v97, 0, v103
	v_max_f32_e32 v99, 0, v99
	v_pk_mul_f32 v[100:101], v[100:101], v[100:101]
	v_pk_mul_f32 v[102:103], v[96:97], v[96:97]
	v_pk_mul_f32 v[106:107], v[98:99], v[98:99]
	v_cvt_pk_bf16_f32 v96, v100, v101
	v_cvt_pk_bf16_f32 v97, v102, v103
	v_cvt_pk_bf16_f32 v98, v104, v105
	v_cvt_pk_bf16_f32 v99, v106, v107
	v_max_f32_e32 v88, 0, v88
	v_max_f32_e32 v89, 0, v89
	v_lshl_add_u64 v[202:203], v[108:109], 0, s[98:99]
	global_store_dwordx4 v[202:203], v[96:99], off
	s_nop 1
	v_or_b32_e32 v96, 32, v150
	v_pk_mul_f32 v[98:99], v[88:89], v[88:89]
	v_ashrrev_i32_e32 v97, 31, v96
	v_max_f32_e32 v92, 0, v92
	v_max_f32_e32 v93, 0, v93
	v_max_f32_e32 v90, 0, v90
	v_lshlrev_b64 v[96:97], 7, v[96:97]
	v_pk_mul_f32 v[92:93], v[92:93], v[92:93]
	v_max_f32_e32 v88, 0, v94
	v_max_f32_e32 v89, 0, v95
	v_max_f32_e32 v91, 0, v91
	v_pk_mul_f32 v[94:95], v[88:89], v[88:89]
	v_pk_mul_f32 v[100:101], v[90:91], v[90:91]
	v_cvt_pk_bf16_f32 v88, v92, v93
	v_lshl_add_u64 v[92:93], s[78:79], 0, v[96:97]
	v_cvt_pk_bf16_f32 v89, v94, v95
	v_cvt_pk_bf16_f32 v90, v98, v99
	v_cvt_pk_bf16_f32 v91, v100, v101
	v_lshl_add_u64 v[92:93], v[92:93], 0, v[126:127]
	v_max_f32_e32 v80, 0, v80
	v_max_f32_e32 v81, 0, v81
	global_store_dwordx4 v[92:93], v[88:91], off
	s_nop 1
	v_pk_mul_f32 v[88:89], v[80:81], v[80:81]
	v_max_f32_e32 v82, 0, v82
	v_max_f32_e32 v84, 0, v84
	v_max_f32_e32 v85, 0, v85
	v_max_f32_e32 v80, 0, v86
	v_max_f32_e32 v81, 0, v87
	v_max_f32_e32 v83, 0, v83
	v_pk_mul_f32 v[84:85], v[84:85], v[84:85]
	v_pk_mul_f32 v[86:87], v[80:81], v[80:81]
	v_pk_mul_f32 v[90:91], v[82:83], v[82:83]
	v_cvt_pk_bf16_f32 v80, v84, v85
	v_cvt_pk_bf16_f32 v81, v86, v87
	v_cvt_pk_bf16_f32 v82, v88, v89
	v_cvt_pk_bf16_f32 v83, v90, v91
	v_max_f32_e32 v72, 0, v72
	v_max_f32_e32 v73, 0, v73
	v_lshl_add_u64 v[204:205], v[92:93], 0, s[98:99]
	global_store_dwordx4 v[204:205], v[80:83], off
	s_nop 1
	v_or_b32_e32 v80, 48, v150
	v_pk_mul_f32 v[82:83], v[72:73], v[72:73]
	v_ashrrev_i32_e32 v81, 31, v80
	v_max_f32_e32 v76, 0, v76
	v_max_f32_e32 v77, 0, v77
	v_max_f32_e32 v74, 0, v74
	v_lshlrev_b64 v[80:81], 7, v[80:81]
	v_pk_mul_f32 v[76:77], v[76:77], v[76:77]
	v_max_f32_e32 v72, 0, v78
	v_max_f32_e32 v73, 0, v79
	v_max_f32_e32 v75, 0, v75
	v_pk_mul_f32 v[78:79], v[72:73], v[72:73]
	v_pk_mul_f32 v[84:85], v[74:75], v[74:75]
	v_cvt_pk_bf16_f32 v72, v76, v77
	v_lshl_add_u64 v[76:77], s[78:79], 0, v[80:81]
	v_cvt_pk_bf16_f32 v73, v78, v79
	v_cvt_pk_bf16_f32 v74, v82, v83
	v_cvt_pk_bf16_f32 v75, v84, v85
	v_lshl_add_u64 v[76:77], v[76:77], 0, v[126:127]
	v_max_f32_e32 v64, 0, v64
	v_max_f32_e32 v65, 0, v65
	global_store_dwordx4 v[76:77], v[72:75], off
	s_nop 1
	v_pk_mul_f32 v[72:73], v[64:65], v[64:65]
	v_max_f32_e32 v66, 0, v66
	v_max_f32_e32 v68, 0, v68
	v_max_f32_e32 v69, 0, v69
	v_max_f32_e32 v64, 0, v70
	v_max_f32_e32 v65, 0, v71
	v_max_f32_e32 v67, 0, v67
	v_pk_mul_f32 v[68:69], v[68:69], v[68:69]
	v_pk_mul_f32 v[70:71], v[64:65], v[64:65]
	v_pk_mul_f32 v[74:75], v[66:67], v[66:67]
	v_cvt_pk_bf16_f32 v64, v68, v69
	v_cvt_pk_bf16_f32 v65, v70, v71
	v_cvt_pk_bf16_f32 v66, v72, v73
	v_cvt_pk_bf16_f32 v67, v74, v75
	v_max_f32_e32 v56, 0, v56
	v_max_f32_e32 v57, 0, v57
	v_lshl_add_u64 v[206:207], v[76:77], 0, s[98:99]
	global_store_dwordx4 v[206:207], v[64:67], off
	s_nop 1
	v_pk_mul_f32 v[64:65], v[56:57], v[56:57]
	v_max_f32_e32 v58, 0, v58
	v_max_f32_e32 v56, 0, v62
	v_max_f32_e32 v57, 0, v63
	v_max_f32_e32 v60, 0, v60
	v_max_f32_e32 v61, 0, v61
	v_max_f32_e32 v59, 0, v59
	v_pk_mul_f32 v[62:63], v[56:57], v[56:57]
	v_pk_mul_f32 v[60:61], v[60:61], v[60:61]
	v_pk_mul_f32 v[66:67], v[58:59], v[58:59]
	v_cvt_pk_bf16_f32 v57, v62, v63
	v_add_co_u32_e32 v62, vcc, s52, v120
	v_cvt_pk_bf16_f32 v56, v60, v61
	v_cvt_pk_bf16_f32 v58, v64, v65
	v_cvt_pk_bf16_f32 v59, v66, v67
	v_addc_co_u32_e32 v63, vcc, 0, v121, vcc
	v_max_f32_e32 v48, 0, v48
	v_max_f32_e32 v49, 0, v49
	global_store_dwordx4 v[62:63], v[56:59], off
	s_nop 1
	v_pk_mul_f32 v[56:57], v[48:49], v[48:49]
	v_max_f32_e32 v50, 0, v50
	v_max_f32_e32 v52, 0, v52
	v_max_f32_e32 v53, 0, v53
	v_max_f32_e32 v48, 0, v54
	v_max_f32_e32 v49, 0, v55
	v_max_f32_e32 v51, 0, v51
	v_pk_mul_f32 v[52:53], v[52:53], v[52:53]
	v_pk_mul_f32 v[54:55], v[48:49], v[48:49]
	v_pk_mul_f32 v[58:59], v[50:51], v[50:51]
	v_lshl_add_u64 v[60:61], v[120:121], 0, s[16:17]
	v_cvt_pk_bf16_f32 v48, v52, v53
	v_cvt_pk_bf16_f32 v49, v54, v55
	v_cvt_pk_bf16_f32 v50, v56, v57
	v_cvt_pk_bf16_f32 v51, v58, v59
	v_max_f32_e32 v40, 0, v40
	v_max_f32_e32 v41, 0, v41
	global_store_dwordx4 v[60:61], v[48:51], off
	s_nop 1
	v_pk_mul_f32 v[48:49], v[40:41], v[40:41]
	v_max_f32_e32 v42, 0, v42
	v_max_f32_e32 v40, 0, v46
	v_max_f32_e32 v41, 0, v47
	v_max_f32_e32 v44, 0, v44
	v_max_f32_e32 v45, 0, v45
	v_max_f32_e32 v43, 0, v43
	v_pk_mul_f32 v[46:47], v[40:41], v[40:41]
	v_pk_mul_f32 v[44:45], v[44:45], v[44:45]
	v_pk_mul_f32 v[50:51], v[42:43], v[42:43]
	v_cvt_pk_bf16_f32 v41, v46, v47
	v_add_co_u32_e32 v46, vcc, s53, v120
	v_cvt_pk_bf16_f32 v40, v44, v45
	v_cvt_pk_bf16_f32 v42, v48, v49
	v_cvt_pk_bf16_f32 v43, v50, v51
	v_addc_co_u32_e32 v47, vcc, 0, v121, vcc
	v_max_f32_e32 v32, 0, v32
	v_max_f32_e32 v33, 0, v33
	global_store_dwordx4 v[46:47], v[40:43], off
	s_nop 1
	v_pk_mul_f32 v[40:41], v[32:33], v[32:33]
	v_max_f32_e32 v34, 0, v34
	v_max_f32_e32 v36, 0, v36
	v_max_f32_e32 v37, 0, v37
	v_max_f32_e32 v32, 0, v38
	v_max_f32_e32 v33, 0, v39
	v_max_f32_e32 v35, 0, v35
	v_pk_mul_f32 v[36:37], v[36:37], v[36:37]
	v_pk_mul_f32 v[38:39], v[32:33], v[32:33]
	v_pk_mul_f32 v[42:43], v[34:35], v[34:35]
	v_lshl_add_u64 v[44:45], v[120:121], 0, s[18:19]
	v_cvt_pk_bf16_f32 v32, v36, v37
	v_cvt_pk_bf16_f32 v33, v38, v39
	v_cvt_pk_bf16_f32 v34, v40, v41
	v_cvt_pk_bf16_f32 v35, v42, v43
	v_max_f32_e32 v24, 0, v24
	v_max_f32_e32 v25, 0, v25
	global_store_dwordx4 v[44:45], v[32:35], off
	s_nop 1
	v_pk_mul_f32 v[32:33], v[24:25], v[24:25]
	v_max_f32_e32 v26, 0, v26
	v_max_f32_e32 v24, 0, v30
	v_max_f32_e32 v25, 0, v31
	v_max_f32_e32 v28, 0, v28
	v_max_f32_e32 v29, 0, v29
	v_max_f32_e32 v27, 0, v27
	v_pk_mul_f32 v[30:31], v[24:25], v[24:25]
	v_pk_mul_f32 v[28:29], v[28:29], v[28:29]
	v_pk_mul_f32 v[34:35], v[26:27], v[26:27]
	v_cvt_pk_bf16_f32 v25, v30, v31
	v_add_co_u32_e32 v30, vcc, s54, v120
	v_cvt_pk_bf16_f32 v24, v28, v29
	v_cvt_pk_bf16_f32 v26, v32, v33
	v_cvt_pk_bf16_f32 v27, v34, v35
	v_addc_co_u32_e32 v31, vcc, 0, v121, vcc
	v_max_f32_e32 v16, 0, v16
	v_max_f32_e32 v17, 0, v17
	global_store_dwordx4 v[30:31], v[24:27], off
	s_nop 1
	v_pk_mul_f32 v[24:25], v[16:17], v[16:17]
	v_max_f32_e32 v18, 0, v18
	v_max_f32_e32 v20, 0, v20
	v_max_f32_e32 v21, 0, v21
	v_max_f32_e32 v16, 0, v22
	v_max_f32_e32 v17, 0, v23
	v_max_f32_e32 v19, 0, v19
	v_pk_mul_f32 v[20:21], v[20:21], v[20:21]
	v_pk_mul_f32 v[22:23], v[16:17], v[16:17]
	v_pk_mul_f32 v[26:27], v[18:19], v[18:19]
	v_lshl_add_u64 v[28:29], v[120:121], 0, s[20:21]
	v_cvt_pk_bf16_f32 v16, v20, v21
	v_cvt_pk_bf16_f32 v17, v22, v23
	v_cvt_pk_bf16_f32 v18, v24, v25
	v_cvt_pk_bf16_f32 v19, v26, v27
	v_max_f32_e32 v8, 0, v8
	v_max_f32_e32 v9, 0, v9
	global_store_dwordx4 v[28:29], v[16:19], off
	s_nop 1
	v_pk_mul_f32 v[16:17], v[8:9], v[8:9]
	v_max_f32_e32 v10, 0, v10
	v_max_f32_e32 v8, 0, v14
	v_max_f32_e32 v9, 0, v15
	v_max_f32_e32 v12, 0, v12
	v_max_f32_e32 v13, 0, v13
	v_max_f32_e32 v11, 0, v11
	v_pk_mul_f32 v[14:15], v[8:9], v[8:9]
	v_pk_mul_f32 v[12:13], v[12:13], v[12:13]
	v_pk_mul_f32 v[18:19], v[10:11], v[10:11]
	v_cvt_pk_bf16_f32 v9, v14, v15
	v_add_co_u32_e32 v14, vcc, s55, v120
	v_cvt_pk_bf16_f32 v8, v12, v13
	v_cvt_pk_bf16_f32 v10, v16, v17
	v_cvt_pk_bf16_f32 v11, v18, v19
	v_addc_co_u32_e32 v15, vcc, 0, v121, vcc
	v_max_f32_e32 v0, 0, v0
	v_max_f32_e32 v1, 0, v1
	global_store_dwordx4 v[14:15], v[8:11], off
	s_nop 1
	v_pk_mul_f32 v[8:9], v[0:1], v[0:1]
	v_max_f32_e32 v2, 0, v2
	v_max_f32_e32 v4, 0, v4
	v_max_f32_e32 v5, 0, v5
	v_max_f32_e32 v0, 0, v6
	v_max_f32_e32 v1, 0, v7
	v_max_f32_e32 v3, 0, v3
	v_pk_mul_f32 v[4:5], v[4:5], v[4:5]
	v_pk_mul_f32 v[6:7], v[0:1], v[0:1]
	v_pk_mul_f32 v[10:11], v[2:3], v[2:3]
	v_lshl_add_u64 v[12:13], v[120:121], 0, s[22:23]
	v_cvt_pk_bf16_f32 v0, v4, v5
	v_cvt_pk_bf16_f32 v1, v6, v7
	v_cvt_pk_bf16_f32 v2, v8, v9
	v_cvt_pk_bf16_f32 v3, v10, v11
	s_andn2_b64 vcc, exec, s[4:5]
	s_mov_b64 s[4:5], -1
	global_store_dwordx4 v[12:13], v[0:3], off
	s_cbranch_vccnz .LBB0_869
	s_andn2_b64 vcc, exec, s[6:7]
	s_cbranch_vccnz .LBB0_868
	s_barrier
	s_branch .LBB0_868
